# the 4 MFMAs before the late opening barrier run at priority 0 (setprio 1 moved behind them), on top of v57
# speedup vs baseline: 1.0002x; 1.0002x over previous
.LBB0_233:
	ds_read_b128 v[130:133], v213
	ds_read_b128 v[134:137], v214
	ds_read_b128 v[138:141], v215
	ds_read_b128 v[142:145], v216
	ds_read_b128 v[146:149], v217
	ds_read_b128 v[150:153], v218
	ds_read_b128 v[154:157], v219
	ds_read_b128 v[158:161], v220
	s_add_i32 s4, s33, 0xffffe080
	s_cmp_eq_u32 s58, 12
	s_cselect_b32 s61, s18, s4
	s_cselect_b32 s60, s19, s57
	s_add_i32 s59, s61, 0x80
	s_mov_b32 s4, s70
	s_mov_b32 m0, s38
	ds_read_b128 v[162:165], v221
	ds_read_b128 v[166:169], v221 offset:2048
	ds_read_b128 v[170:173], v222
	ds_read_b128 v[174:177], v222 offset:2048
	ds_read_b128 v[178:181], v221 offset:4096
	ds_read_b128 v[182:185], v221 offset:6144
	ds_read_b128 v[186:189], v222 offset:4096
	ds_read_b128 v[190:193], v222 offset:6144
	buffer_load_dwordx4 v207, s[4:7], s33 offen lds
	s_mov_b32 m0, s41
	s_nop 0
	buffer_load_dwordx4 v209, s[4:7], s33 offen lds
	s_waitcnt vmcnt(8)
	s_waitcnt lgkmcnt(0)
	v_mfma_f32_16x16x32_bf16 v[114:117], v[130:133], v[162:165], v[114:117]
	v_mfma_f32_16x16x32_bf16 v[110:113], v[138:141], v[162:165], v[110:113]
	v_mfma_f32_16x16x32_bf16 v[106:109], v[130:133], v[166:169], v[106:109]
	v_mfma_f32_16x16x32_bf16 v[102:105], v[138:141], v[166:169], v[102:105]
	s_setprio 1
	s_barrier
	v_mfma_f32_16x16x32_bf16 v[98:101], v[130:133], v[178:181], v[98:101]
	v_mfma_f32_16x16x32_bf16 v[94:97], v[138:141], v[178:181], v[94:97]
	v_mfma_f32_16x16x32_bf16 v[90:93], v[130:133], v[182:185], v[90:93]
	v_mfma_f32_16x16x32_bf16 v[86:89], v[138:141], v[182:185], v[86:89]
	v_mfma_f32_16x16x32_bf16 v[114:117], v[134:137], v[170:173], v[114:117]
	v_mfma_f32_16x16x32_bf16 v[110:113], v[142:145], v[170:173], v[110:113]
	v_mfma_f32_16x16x32_bf16 v[106:109], v[134:137], v[174:177], v[106:109]
	v_mfma_f32_16x16x32_bf16 v[102:105], v[142:145], v[174:177], v[102:105]
	v_mfma_f32_16x16x32_bf16 v[98:101], v[134:137], v[186:189], v[98:101]
	v_mfma_f32_16x16x32_bf16 v[94:97], v[142:145], v[186:189], v[94:97]
	v_mfma_f32_16x16x32_bf16 v[90:93], v[134:137], v[190:193], v[90:93]
	v_mfma_f32_16x16x32_bf16 v[86:89], v[142:145], v[190:193], v[86:89]
	v_mfma_f32_16x16x32_bf16 v[82:85], v[146:149], v[162:165], v[82:85]
	v_mfma_f32_16x16x32_bf16 v[74:77], v[154:157], v[162:165], v[74:77]
	v_mfma_f32_16x16x32_bf16 v[70:73], v[146:149], v[166:169], v[70:73]
	v_mfma_f32_16x16x32_bf16 v[66:69], v[154:157], v[166:169], v[66:69]
	v_mfma_f32_16x16x32_bf16 v[62:65], v[146:149], v[178:181], v[62:65]
	v_mfma_f32_16x16x32_bf16 v[58:61], v[154:157], v[178:181], v[58:61]
	v_mfma_f32_16x16x32_bf16 v[54:57], v[146:149], v[182:185], v[54:57]
	v_mfma_f32_16x16x32_bf16 v[50:53], v[154:157], v[182:185], v[50:53]
	v_mfma_f32_16x16x32_bf16 v[82:85], v[150:153], v[170:173], v[82:85]
	v_mfma_f32_16x16x32_bf16 v[74:77], v[158:161], v[170:173], v[74:77]
	v_mfma_f32_16x16x32_bf16 v[70:73], v[150:153], v[174:177], v[70:73]
	v_mfma_f32_16x16x32_bf16 v[66:69], v[158:161], v[174:177], v[66:69]
	v_mfma_f32_16x16x32_bf16 v[62:65], v[150:153], v[186:189], v[62:65]
	v_mfma_f32_16x16x32_bf16 v[58:61], v[158:161], v[186:189], v[58:61]
	v_mfma_f32_16x16x32_bf16 v[54:57], v[150:153], v[190:193], v[54:57]
	v_mfma_f32_16x16x32_bf16 v[50:53], v[158:161], v[190:193], v[50:53]
	s_barrier
	s_setprio 0
	s_mov_b32 m0, s21
	ds_read_b128 v[162:165], v221 offset:16384
	ds_read_b128 v[166:169], v221 offset:18432
	ds_read_b128 v[170:173], v222 offset:16384
	ds_read_b128 v[174:177], v222 offset:18432
	ds_read_b128 v[178:181], v221 offset:20480
	ds_read_b128 v[182:185], v221 offset:22528
	ds_read_b128 v[186:189], v222 offset:20480
	ds_read_b128 v[190:193], v222 offset:22528
	buffer_load_dwordx4 v208, s[4:7], s60 offen lds
	s_mov_b32 m0, s22
	s_add_i32 s62, s60, 0x40000
	buffer_load_dwordx4 v210, s[4:7], s60 offen lds
	s_mov_b32 m0, s23
	s_nop 0
	buffer_load_dwordx4 v208, s[4:7], s62 offen lds
	s_mov_b32 m0, s24
	s_nop 0
	buffer_load_dwordx4 v210, s[4:7], s62 offen lds
	s_mov_b32 m0, s20
	s_nop 0
	buffer_load_dwordx4 v207, s[4:7], s61 offen lds
	s_mov_b32 m0, s25
	s_nop 0
	buffer_load_dwordx4 v209, s[4:7], s61 offen lds
	s_waitcnt vmcnt(8)
	s_waitcnt lgkmcnt(0)
	s_setprio 1
	s_barrier
	v_mfma_f32_16x16x32_bf16 v[78:81], v[130:133], v[162:165], v[78:81]
	v_mfma_f32_16x16x32_bf16 v[46:49], v[138:141], v[162:165], v[46:49]
	v_mfma_f32_16x16x32_bf16 v[42:45], v[130:133], v[166:169], v[42:45]
	v_mfma_f32_16x16x32_bf16 v[38:41], v[138:141], v[166:169], v[38:41]
	v_mfma_f32_16x16x32_bf16 v[34:37], v[130:133], v[178:181], v[34:37]
	v_mfma_f32_16x16x32_bf16 v[30:33], v[138:141], v[178:181], v[30:33]
	v_mfma_f32_16x16x32_bf16 v[26:29], v[130:133], v[182:185], v[26:29]
	v_mfma_f32_16x16x32_bf16 v[22:25], v[138:141], v[182:185], v[22:25]
	v_mfma_f32_16x16x32_bf16 v[78:81], v[134:137], v[170:173], v[78:81]
	v_mfma_f32_16x16x32_bf16 v[46:49], v[142:145], v[170:173], v[46:49]
	v_mfma_f32_16x16x32_bf16 v[42:45], v[134:137], v[174:177], v[42:45]
	v_mfma_f32_16x16x32_bf16 v[38:41], v[142:145], v[174:177], v[38:41]
	v_mfma_f32_16x16x32_bf16 v[34:37], v[134:137], v[186:189], v[34:37]
	v_mfma_f32_16x16x32_bf16 v[30:33], v[142:145], v[186:189], v[30:33]
	v_mfma_f32_16x16x32_bf16 v[26:29], v[134:137], v[190:193], v[26:29]
	v_mfma_f32_16x16x32_bf16 v[22:25], v[142:145], v[190:193], v[22:25]
	v_mfma_f32_16x16x32_bf16 v[18:21], v[146:149], v[162:165], v[18:21]
	v_mfma_f32_16x16x32_bf16 v[14:17], v[154:157], v[162:165], v[14:17]
	v_mfma_f32_16x16x32_bf16 v[10:13], v[146:149], v[166:169], v[10:13]
	v_mfma_f32_16x16x32_bf16 v[6:9], v[154:157], v[166:169], v[6:9]
	v_mfma_f32_16x16x32_bf16 v[2:5], v[146:149], v[178:181], v[2:5]
	v_mfma_f32_16x16x32_bf16 v[126:129], v[154:157], v[178:181], v[126:129]
	v_mfma_f32_16x16x32_bf16 v[122:125], v[146:149], v[182:185], v[122:125]
	v_mfma_f32_16x16x32_bf16 v[118:121], v[154:157], v[182:185], v[118:121]
	v_mfma_f32_16x16x32_bf16 v[18:21], v[150:153], v[170:173], v[18:21]
	v_mfma_f32_16x16x32_bf16 v[14:17], v[158:161], v[170:173], v[14:17]
	v_mfma_f32_16x16x32_bf16 v[10:13], v[150:153], v[174:177], v[10:13]
	v_mfma_f32_16x16x32_bf16 v[6:9], v[158:161], v[174:177], v[6:9]
	v_mfma_f32_16x16x32_bf16 v[2:5], v[150:153], v[186:189], v[2:5]
	v_mfma_f32_16x16x32_bf16 v[126:129], v[158:161], v[186:189], v[126:129]
	v_mfma_f32_16x16x32_bf16 v[122:125], v[150:153], v[190:193], v[122:125]
	v_mfma_f32_16x16x32_bf16 v[118:121], v[158:161], v[190:193], v[118:121]
	s_barrier
	s_setprio 0
	ds_read_b128 v[130:133], v194
	ds_read_b128 v[134:137], v224
	ds_read_b128 v[138:141], v225
	ds_read_b128 v[142:145], v228
	ds_read_b128 v[146:149], v229
	ds_read_b128 v[150:153], v230
	ds_read_b128 v[154:157], v231
	ds_read_b128 v[158:161], v233
	s_addk_i32 s61, 0x2000
	s_mov_b32 m0, s26
	ds_read_b128 v[162:165], v221 offset:32768
	ds_read_b128 v[166:169], v221 offset:34816
	ds_read_b128 v[170:173], v222 offset:32768
	ds_read_b128 v[174:177], v222 offset:34816
	ds_read_b128 v[178:181], v221 offset:36864
	ds_read_b128 v[182:185], v221 offset:38912
	ds_read_b128 v[186:189], v222 offset:36864
	ds_read_b128 v[190:193], v222 offset:38912
	buffer_load_dwordx4 v207, s[4:7], s61 offen lds
	s_mov_b32 m0, s27
	s_nop 0
	buffer_load_dwordx4 v209, s[4:7], s61 offen lds
	s_waitcnt vmcnt(8)
	s_waitcnt lgkmcnt(0)
	v_mfma_f32_16x16x32_bf16 v[114:117], v[130:133], v[162:165], v[114:117]
	v_mfma_f32_16x16x32_bf16 v[110:113], v[138:141], v[162:165], v[110:113]
	v_mfma_f32_16x16x32_bf16 v[106:109], v[130:133], v[166:169], v[106:109]
	v_mfma_f32_16x16x32_bf16 v[102:105], v[138:141], v[166:169], v[102:105]
	s_setprio 1
	s_barrier
	v_mfma_f32_16x16x32_bf16 v[98:101], v[130:133], v[178:181], v[98:101]
	v_mfma_f32_16x16x32_bf16 v[94:97], v[138:141], v[178:181], v[94:97]
	v_mfma_f32_16x16x32_bf16 v[90:93], v[130:133], v[182:185], v[90:93]
	v_mfma_f32_16x16x32_bf16 v[86:89], v[138:141], v[182:185], v[86:89]
	v_mfma_f32_16x16x32_bf16 v[114:117], v[134:137], v[170:173], v[114:117]
	v_mfma_f32_16x16x32_bf16 v[110:113], v[142:145], v[170:173], v[110:113]
	v_mfma_f32_16x16x32_bf16 v[106:109], v[134:137], v[174:177], v[106:109]
	v_mfma_f32_16x16x32_bf16 v[102:105], v[142:145], v[174:177], v[102:105]
	v_mfma_f32_16x16x32_bf16 v[98:101], v[134:137], v[186:189], v[98:101]
	v_mfma_f32_16x16x32_bf16 v[94:97], v[142:145], v[186:189], v[94:97]
	v_mfma_f32_16x16x32_bf16 v[90:93], v[134:137], v[190:193], v[90:93]
	v_mfma_f32_16x16x32_bf16 v[86:89], v[142:145], v[190:193], v[86:89]
	v_mfma_f32_16x16x32_bf16 v[82:85], v[146:149], v[162:165], v[82:85]
	v_mfma_f32_16x16x32_bf16 v[74:77], v[154:157], v[162:165], v[74:77]
	v_mfma_f32_16x16x32_bf16 v[70:73], v[146:149], v[166:169], v[70:73]
	v_mfma_f32_16x16x32_bf16 v[66:69], v[154:157], v[166:169], v[66:69]
	v_mfma_f32_16x16x32_bf16 v[62:65], v[146:149], v[178:181], v[62:65]
	v_mfma_f32_16x16x32_bf16 v[58:61], v[154:157], v[178:181], v[58:61]
	v_mfma_f32_16x16x32_bf16 v[54:57], v[146:149], v[182:185], v[54:57]
	v_mfma_f32_16x16x32_bf16 v[50:53], v[154:157], v[182:185], v[50:53]
	v_mfma_f32_16x16x32_bf16 v[82:85], v[150:153], v[170:173], v[82:85]
	v_mfma_f32_16x16x32_bf16 v[74:77], v[158:161], v[170:173], v[74:77]
	v_mfma_f32_16x16x32_bf16 v[70:73], v[150:153], v[174:177], v[70:73]
	v_mfma_f32_16x16x32_bf16 v[66:69], v[158:161], v[174:177], v[66:69]
	v_mfma_f32_16x16x32_bf16 v[62:65], v[150:153], v[186:189], v[62:65]
	v_mfma_f32_16x16x32_bf16 v[58:61], v[158:161], v[186:189], v[58:61]
	v_mfma_f32_16x16x32_bf16 v[54:57], v[150:153], v[190:193], v[54:57]
	v_mfma_f32_16x16x32_bf16 v[50:53], v[158:161], v[190:193], v[50:53]
	s_barrier
	s_setprio 0
	s_mov_b32 m0, s29
	s_add_i32 s61, s60, 0x80
	ds_read_b128 v[162:165], v221 offset:49152
	ds_read_b128 v[166:169], v221 offset:51200
	ds_read_b128 v[170:173], v222 offset:49152
	ds_read_b128 v[174:177], v222 offset:51200
	ds_read_b128 v[178:181], v221 offset:53248
	ds_read_b128 v[182:185], v221 offset:55296
	ds_read_b128 v[186:189], v222 offset:53248
	ds_read_b128 v[190:193], v222 offset:55296
	buffer_load_dwordx4 v208, s[4:7], s61 offen lds
	s_mov_b32 m0, s30
	s_add_i32 s60, s60, 0x40080
	buffer_load_dwordx4 v210, s[4:7], s61 offen lds
	s_mov_b32 m0, s35
	s_nop 0
	buffer_load_dwordx4 v208, s[4:7], s60 offen lds
	s_mov_b32 m0, s36
	s_nop 0
	buffer_load_dwordx4 v210, s[4:7], s60 offen lds
	s_mov_b32 m0, s31
	s_nop 0
	buffer_load_dwordx4 v207, s[4:7], s59 offen lds
	s_mov_b32 m0, s34
	s_nop 0
	buffer_load_dwordx4 v209, s[4:7], s59 offen lds
	s_waitcnt vmcnt(8)
	s_waitcnt lgkmcnt(0)
	s_setprio 1
	s_barrier
	v_mfma_f32_16x16x32_bf16 v[78:81], v[130:133], v[162:165], v[78:81]
	v_mfma_f32_16x16x32_bf16 v[46:49], v[138:141], v[162:165], v[46:49]
	v_mfma_f32_16x16x32_bf16 v[42:45], v[130:133], v[166:169], v[42:45]
	v_mfma_f32_16x16x32_bf16 v[38:41], v[138:141], v[166:169], v[38:41]
	v_mfma_f32_16x16x32_bf16 v[34:37], v[130:133], v[178:181], v[34:37]
	v_mfma_f32_16x16x32_bf16 v[30:33], v[138:141], v[178:181], v[30:33]
	v_mfma_f32_16x16x32_bf16 v[26:29], v[130:133], v[182:185], v[26:29]
	v_mfma_f32_16x16x32_bf16 v[22:25], v[138:141], v[182:185], v[22:25]
	v_mfma_f32_16x16x32_bf16 v[78:81], v[134:137], v[170:173], v[78:81]
	v_mfma_f32_16x16x32_bf16 v[46:49], v[142:145], v[170:173], v[46:49]
	v_mfma_f32_16x16x32_bf16 v[42:45], v[134:137], v[174:177], v[42:45]
	v_mfma_f32_16x16x32_bf16 v[38:41], v[142:145], v[174:177], v[38:41]
	v_mfma_f32_16x16x32_bf16 v[34:37], v[134:137], v[186:189], v[34:37]
	v_mfma_f32_16x16x32_bf16 v[30:33], v[142:145], v[186:189], v[30:33]
	v_mfma_f32_16x16x32_bf16 v[26:29], v[134:137], v[190:193], v[26:29]
	v_mfma_f32_16x16x32_bf16 v[22:25], v[142:145], v[190:193], v[22:25]
	v_mfma_f32_16x16x32_bf16 v[18:21], v[146:149], v[162:165], v[18:21]
	v_mfma_f32_16x16x32_bf16 v[14:17], v[154:157], v[162:165], v[14:17]
	v_mfma_f32_16x16x32_bf16 v[10:13], v[146:149], v[166:169], v[10:13]
	v_mfma_f32_16x16x32_bf16 v[6:9], v[154:157], v[166:169], v[6:9]
	v_mfma_f32_16x16x32_bf16 v[2:5], v[146:149], v[178:181], v[2:5]
	v_mfma_f32_16x16x32_bf16 v[126:129], v[154:157], v[178:181], v[126:129]
	v_mfma_f32_16x16x32_bf16 v[122:125], v[146:149], v[182:185], v[122:125]
	v_mfma_f32_16x16x32_bf16 v[118:121], v[154:157], v[182:185], v[118:121]
	v_mfma_f32_16x16x32_bf16 v[18:21], v[150:153], v[170:173], v[18:21]
	v_mfma_f32_16x16x32_bf16 v[14:17], v[158:161], v[170:173], v[14:17]
	v_mfma_f32_16x16x32_bf16 v[10:13], v[150:153], v[174:177], v[10:13]
	v_mfma_f32_16x16x32_bf16 v[6:9], v[158:161], v[174:177], v[6:9]
	v_mfma_f32_16x16x32_bf16 v[2:5], v[150:153], v[186:189], v[2:5]
	v_mfma_f32_16x16x32_bf16 v[126:129], v[158:161], v[186:189], v[126:129]
	v_mfma_f32_16x16x32_bf16 v[122:125], v[150:153], v[190:193], v[122:125]
	v_mfma_f32_16x16x32_bf16 v[118:121], v[158:161], v[190:193], v[118:121]
	s_barrier
	s_setprio 0
	s_add_i32 s58, s58, 2
	s_addk_i32 s33, 0x100
	s_addk_i32 s57, 0x100
	s_cmp_gt_u32 s58, 13
	s_cbranch_scc0 .LBB0_233
	s_and_b64 vcc, exec, s[16:17]
	s_cbranch_vccz .LBB0_236
	s_barrier

.LBB0_546:
	ds_read_b128 v[130:133], v211
	ds_read_b128 v[134:137], v212
	ds_read_b128 v[138:141], v213
	ds_read_b128 v[142:145], v214
	ds_read_b128 v[146:149], v215
	ds_read_b128 v[150:153], v216
	ds_read_b128 v[154:157], v217
	ds_read_b128 v[158:161], v218
	s_add_i32 s4, s62, 0x80
	s_cmp_eq_u32 s63, s78
	s_cselect_b32 s84, s64, s4
	s_cselect_b32 s82, s33, s59
	s_cselect_b32 s81, s65, s61
	s_cselect_b32 s80, s56, s60
	s_add_i32 s79, s84, 0x80
	s_add_i32 s83, s60, s62
	s_mov_b32 s4, s70
	s_mov_b32 m0, s43
	ds_read_b128 v[162:165], v219
	ds_read_b128 v[166:169], v219 offset:2048
	ds_read_b128 v[170:173], v220
	ds_read_b128 v[174:177], v220 offset:2048
	ds_read_b128 v[178:181], v219 offset:4096
	ds_read_b128 v[182:185], v219 offset:6144
	ds_read_b128 v[186:189], v220 offset:4096
	ds_read_b128 v[190:193], v220 offset:6144
	buffer_load_dwordx4 v194, s[4:7], s83 offen lds
	s_mov_b32 m0, s44
	s_nop 0
	buffer_load_dwordx4 v222, s[4:7], s83 offen lds
	s_waitcnt vmcnt(8)
	s_waitcnt lgkmcnt(0)
	v_mfma_f32_16x16x32_bf16 v[126:129], v[130:133], v[162:165], v[126:129]
	v_mfma_f32_16x16x32_bf16 v[122:125], v[138:141], v[162:165], v[122:125]
	v_mfma_f32_16x16x32_bf16 v[118:121], v[130:133], v[166:169], v[118:121]
	v_mfma_f32_16x16x32_bf16 v[114:117], v[138:141], v[166:169], v[114:117]
	s_setprio 1
	s_barrier
	v_mfma_f32_16x16x32_bf16 v[110:113], v[130:133], v[178:181], v[110:113]
	v_mfma_f32_16x16x32_bf16 v[106:109], v[138:141], v[178:181], v[106:109]
	v_mfma_f32_16x16x32_bf16 v[102:105], v[130:133], v[182:185], v[102:105]
	v_mfma_f32_16x16x32_bf16 v[98:101], v[138:141], v[182:185], v[98:101]
	v_mfma_f32_16x16x32_bf16 v[126:129], v[134:137], v[170:173], v[126:129]
	v_mfma_f32_16x16x32_bf16 v[122:125], v[142:145], v[170:173], v[122:125]
	v_mfma_f32_16x16x32_bf16 v[118:121], v[134:137], v[174:177], v[118:121]
	v_mfma_f32_16x16x32_bf16 v[114:117], v[142:145], v[174:177], v[114:117]
	v_mfma_f32_16x16x32_bf16 v[110:113], v[134:137], v[186:189], v[110:113]
	v_mfma_f32_16x16x32_bf16 v[106:109], v[142:145], v[186:189], v[106:109]
	v_mfma_f32_16x16x32_bf16 v[102:105], v[134:137], v[190:193], v[102:105]
	v_mfma_f32_16x16x32_bf16 v[98:101], v[142:145], v[190:193], v[98:101]
	v_mfma_f32_16x16x32_bf16 v[94:97], v[146:149], v[162:165], v[94:97]
	v_mfma_f32_16x16x32_bf16 v[90:93], v[154:157], v[162:165], v[90:93]
	v_mfma_f32_16x16x32_bf16 v[86:89], v[146:149], v[166:169], v[86:89]
	v_mfma_f32_16x16x32_bf16 v[82:85], v[154:157], v[166:169], v[82:85]
	v_mfma_f32_16x16x32_bf16 v[78:81], v[146:149], v[178:181], v[78:81]
	v_mfma_f32_16x16x32_bf16 v[74:77], v[154:157], v[178:181], v[74:77]
	v_mfma_f32_16x16x32_bf16 v[70:73], v[146:149], v[182:185], v[70:73]
	v_mfma_f32_16x16x32_bf16 v[66:69], v[154:157], v[182:185], v[66:69]
	v_mfma_f32_16x16x32_bf16 v[94:97], v[150:153], v[170:173], v[94:97]
	v_mfma_f32_16x16x32_bf16 v[90:93], v[158:161], v[170:173], v[90:93]
	v_mfma_f32_16x16x32_bf16 v[86:89], v[150:153], v[174:177], v[86:89]
	v_mfma_f32_16x16x32_bf16 v[82:85], v[158:161], v[174:177], v[82:85]
	v_mfma_f32_16x16x32_bf16 v[78:81], v[150:153], v[186:189], v[78:81]
	v_mfma_f32_16x16x32_bf16 v[74:77], v[158:161], v[186:189], v[74:77]
	v_mfma_f32_16x16x32_bf16 v[70:73], v[150:153], v[190:193], v[70:73]
	v_mfma_f32_16x16x32_bf16 v[66:69], v[158:161], v[190:193], v[66:69]
	s_barrier
	s_setprio 0
	s_cmp_eq_u32 s82, 0
	s_cselect_b64 s[82:83], -1, 0
	v_cndmask_b32_e64 v233, v200, 0, s[82:83]
	s_mov_b32 m0, s25
	v_sub_u32_e32 v233, v201, v233
	v_cndmask_b32_e64 v234, v203, 0, s[82:83]
	ds_read_b128 v[162:165], v219 offset:16384
	ds_read_b128 v[166:169], v219 offset:18432
	ds_read_b128 v[170:173], v220 offset:16384
	ds_read_b128 v[174:177], v220 offset:18432
	ds_read_b128 v[178:181], v219 offset:20480
	ds_read_b128 v[182:185], v219 offset:22528
	ds_read_b128 v[186:189], v220 offset:20480
	ds_read_b128 v[190:193], v220 offset:22528
	buffer_load_dwordx4 v233, s[4:7], s81 offen lds
	v_sub_u32_e32 v234, v204, v234
	s_mov_b32 m0, s26
	s_add_i32 s85, s81, s80
	buffer_load_dwordx4 v234, s[4:7], s81 offen lds
	s_mov_b32 m0, s27
	v_cndmask_b32_e64 v235, v205, 0, s[82:83]
	buffer_load_dwordx4 v233, s[4:7], s85 offen lds
	s_mov_b32 m0, s28
	v_sub_u32_e32 v235, v1, v235
	buffer_load_dwordx4 v234, s[4:7], s85 offen lds
	s_mov_b32 m0, s24
	v_cndmask_b32_e64 v236, v206, 0, s[82:83]
	buffer_load_dwordx4 v235, s[4:7], s84 offen lds
	v_sub_u32_e32 v236, v202, v236
	s_mov_b32 m0, s29
	s_nop 0
	buffer_load_dwordx4 v236, s[4:7], s84 offen lds
	s_waitcnt vmcnt(8)
	s_waitcnt lgkmcnt(0)
	s_setprio 1
	s_barrier
	v_mfma_f32_16x16x32_bf16 v[62:65], v[130:133], v[162:165], v[62:65]
	v_mfma_f32_16x16x32_bf16 v[58:61], v[138:141], v[162:165], v[58:61]
	v_mfma_f32_16x16x32_bf16 v[54:57], v[130:133], v[166:169], v[54:57]
	v_mfma_f32_16x16x32_bf16 v[50:53], v[138:141], v[166:169], v[50:53]
	v_mfma_f32_16x16x32_bf16 v[46:49], v[130:133], v[178:181], v[46:49]
	v_mfma_f32_16x16x32_bf16 v[42:45], v[138:141], v[178:181], v[42:45]
	v_mfma_f32_16x16x32_bf16 v[38:41], v[130:133], v[182:185], v[38:41]
	v_mfma_f32_16x16x32_bf16 v[34:37], v[138:141], v[182:185], v[34:37]
	v_mfma_f32_16x16x32_bf16 v[62:65], v[134:137], v[170:173], v[62:65]
	v_mfma_f32_16x16x32_bf16 v[58:61], v[142:145], v[170:173], v[58:61]
	v_mfma_f32_16x16x32_bf16 v[54:57], v[134:137], v[174:177], v[54:57]
	v_mfma_f32_16x16x32_bf16 v[50:53], v[142:145], v[174:177], v[50:53]
	v_mfma_f32_16x16x32_bf16 v[46:49], v[134:137], v[186:189], v[46:49]
	v_mfma_f32_16x16x32_bf16 v[42:45], v[142:145], v[186:189], v[42:45]
	v_mfma_f32_16x16x32_bf16 v[38:41], v[134:137], v[190:193], v[38:41]
	v_mfma_f32_16x16x32_bf16 v[34:37], v[142:145], v[190:193], v[34:37]
	v_mfma_f32_16x16x32_bf16 v[30:33], v[146:149], v[162:165], v[30:33]
	v_mfma_f32_16x16x32_bf16 v[26:29], v[154:157], v[162:165], v[26:29]
	v_mfma_f32_16x16x32_bf16 v[22:25], v[146:149], v[166:169], v[22:25]
	v_mfma_f32_16x16x32_bf16 v[18:21], v[154:157], v[166:169], v[18:21]
	v_mfma_f32_16x16x32_bf16 v[14:17], v[146:149], v[178:181], v[14:17]
	v_mfma_f32_16x16x32_bf16 v[10:13], v[154:157], v[178:181], v[10:13]
	v_mfma_f32_16x16x32_bf16 v[6:9], v[146:149], v[182:185], v[6:9]
	v_mfma_f32_16x16x32_bf16 v[2:5], v[154:157], v[182:185], v[2:5]
	v_mfma_f32_16x16x32_bf16 v[30:33], v[150:153], v[170:173], v[30:33]
	v_mfma_f32_16x16x32_bf16 v[26:29], v[158:161], v[170:173], v[26:29]
	v_mfma_f32_16x16x32_bf16 v[22:25], v[150:153], v[174:177], v[22:25]
	v_mfma_f32_16x16x32_bf16 v[18:21], v[158:161], v[174:177], v[18:21]
	v_mfma_f32_16x16x32_bf16 v[14:17], v[150:153], v[186:189], v[14:17]
	v_mfma_f32_16x16x32_bf16 v[10:13], v[158:161], v[186:189], v[10:13]
	v_mfma_f32_16x16x32_bf16 v[6:9], v[150:153], v[190:193], v[6:9]
	v_mfma_f32_16x16x32_bf16 v[2:5], v[158:161], v[190:193], v[2:5]
	s_barrier
	s_setprio 0
	ds_read_b128 v[130:133], v223
	ds_read_b128 v[134:137], v224
	ds_read_b128 v[138:141], v225
	ds_read_b128 v[142:145], v227
	ds_read_b128 v[146:149], v228
	ds_read_b128 v[150:153], v229
	ds_read_b128 v[154:157], v230
	ds_read_b128 v[158:161], v231
	s_add_i32 s84, s84, s80
	s_mov_b32 m0, s30
	ds_read_b128 v[162:165], v219 offset:32768
	ds_read_b128 v[166:169], v219 offset:34816
	ds_read_b128 v[170:173], v220 offset:32768
	ds_read_b128 v[174:177], v220 offset:34816
	ds_read_b128 v[178:181], v219 offset:36864
	ds_read_b128 v[182:185], v219 offset:38912
	ds_read_b128 v[186:189], v220 offset:36864
	ds_read_b128 v[190:193], v220 offset:38912
	buffer_load_dwordx4 v235, s[4:7], s84 offen lds
	s_mov_b32 m0, s31
	s_nop 0
	buffer_load_dwordx4 v236, s[4:7], s84 offen lds
	s_waitcnt vmcnt(8)
	s_waitcnt lgkmcnt(0)
	v_mfma_f32_16x16x32_bf16 v[126:129], v[130:133], v[162:165], v[126:129]
	v_mfma_f32_16x16x32_bf16 v[122:125], v[138:141], v[162:165], v[122:125]
	v_mfma_f32_16x16x32_bf16 v[118:121], v[130:133], v[166:169], v[118:121]
	v_mfma_f32_16x16x32_bf16 v[114:117], v[138:141], v[166:169], v[114:117]
	s_setprio 1
	s_barrier
	v_mfma_f32_16x16x32_bf16 v[110:113], v[130:133], v[178:181], v[110:113]
	v_mfma_f32_16x16x32_bf16 v[106:109], v[138:141], v[178:181], v[106:109]
	v_mfma_f32_16x16x32_bf16 v[102:105], v[130:133], v[182:185], v[102:105]
	v_mfma_f32_16x16x32_bf16 v[98:101], v[138:141], v[182:185], v[98:101]
	v_mfma_f32_16x16x32_bf16 v[126:129], v[134:137], v[170:173], v[126:129]
	v_mfma_f32_16x16x32_bf16 v[122:125], v[142:145], v[170:173], v[122:125]
	v_mfma_f32_16x16x32_bf16 v[118:121], v[134:137], v[174:177], v[118:121]
	v_mfma_f32_16x16x32_bf16 v[114:117], v[142:145], v[174:177], v[114:117]
	v_mfma_f32_16x16x32_bf16 v[110:113], v[134:137], v[186:189], v[110:113]
	v_mfma_f32_16x16x32_bf16 v[106:109], v[142:145], v[186:189], v[106:109]
	v_mfma_f32_16x16x32_bf16 v[102:105], v[134:137], v[190:193], v[102:105]
	v_mfma_f32_16x16x32_bf16 v[98:101], v[142:145], v[190:193], v[98:101]
	v_mfma_f32_16x16x32_bf16 v[94:97], v[146:149], v[162:165], v[94:97]
	v_mfma_f32_16x16x32_bf16 v[90:93], v[154:157], v[162:165], v[90:93]
	v_mfma_f32_16x16x32_bf16 v[86:89], v[146:149], v[166:169], v[86:89]
	v_mfma_f32_16x16x32_bf16 v[82:85], v[154:157], v[166:169], v[82:85]
	v_mfma_f32_16x16x32_bf16 v[78:81], v[146:149], v[178:181], v[78:81]
	v_mfma_f32_16x16x32_bf16 v[74:77], v[154:157], v[178:181], v[74:77]
	v_mfma_f32_16x16x32_bf16 v[70:73], v[146:149], v[182:185], v[70:73]
	v_mfma_f32_16x16x32_bf16 v[66:69], v[154:157], v[182:185], v[66:69]
	v_mfma_f32_16x16x32_bf16 v[94:97], v[150:153], v[170:173], v[94:97]
	v_mfma_f32_16x16x32_bf16 v[90:93], v[158:161], v[170:173], v[90:93]
	v_mfma_f32_16x16x32_bf16 v[86:89], v[150:153], v[174:177], v[86:89]
	v_mfma_f32_16x16x32_bf16 v[82:85], v[158:161], v[174:177], v[82:85]
	v_mfma_f32_16x16x32_bf16 v[78:81], v[150:153], v[186:189], v[78:81]
	v_mfma_f32_16x16x32_bf16 v[74:77], v[158:161], v[186:189], v[74:77]
	v_mfma_f32_16x16x32_bf16 v[70:73], v[150:153], v[190:193], v[70:73]
	v_mfma_f32_16x16x32_bf16 v[66:69], v[158:161], v[190:193], v[66:69]
	s_barrier
	s_setprio 0
	s_mov_b32 m0, s36
	s_addk_i32 s81, 0x80
	ds_read_b128 v[162:165], v219 offset:49152
	ds_read_b128 v[166:169], v219 offset:51200
	ds_read_b128 v[170:173], v220 offset:49152
	ds_read_b128 v[174:177], v220 offset:51200
	ds_read_b128 v[178:181], v219 offset:53248
	ds_read_b128 v[182:185], v219 offset:55296
	ds_read_b128 v[186:189], v220 offset:53248
	ds_read_b128 v[190:193], v220 offset:55296
	buffer_load_dwordx4 v233, s[4:7], s81 offen lds
	s_mov_b32 m0, s37
	s_nop 0
	buffer_load_dwordx4 v234, s[4:7], s81 offen lds
	s_add_i32 s81, s81, s80
	s_mov_b32 m0, s40
	s_nop 0
	buffer_load_dwordx4 v233, s[4:7], s81 offen lds
	s_mov_b32 m0, s41
	s_nop 0
	buffer_load_dwordx4 v234, s[4:7], s81 offen lds
	s_mov_b32 m0, s38
	s_nop 0
	buffer_load_dwordx4 v235, s[4:7], s79 offen lds
	s_mov_b32 m0, s39
	s_nop 0
	buffer_load_dwordx4 v236, s[4:7], s79 offen lds
	s_waitcnt vmcnt(8)
	s_waitcnt lgkmcnt(0)
	s_setprio 1
	s_barrier
	v_mfma_f32_16x16x32_bf16 v[62:65], v[130:133], v[162:165], v[62:65]
	v_mfma_f32_16x16x32_bf16 v[58:61], v[138:141], v[162:165], v[58:61]
	v_mfma_f32_16x16x32_bf16 v[54:57], v[130:133], v[166:169], v[54:57]
	v_mfma_f32_16x16x32_bf16 v[50:53], v[138:141], v[166:169], v[50:53]
	v_mfma_f32_16x16x32_bf16 v[46:49], v[130:133], v[178:181], v[46:49]
	v_mfma_f32_16x16x32_bf16 v[42:45], v[138:141], v[178:181], v[42:45]
	v_mfma_f32_16x16x32_bf16 v[38:41], v[130:133], v[182:185], v[38:41]
	v_mfma_f32_16x16x32_bf16 v[34:37], v[138:141], v[182:185], v[34:37]
	v_mfma_f32_16x16x32_bf16 v[62:65], v[134:137], v[170:173], v[62:65]
	v_mfma_f32_16x16x32_bf16 v[58:61], v[142:145], v[170:173], v[58:61]
	v_mfma_f32_16x16x32_bf16 v[54:57], v[134:137], v[174:177], v[54:57]
	v_mfma_f32_16x16x32_bf16 v[50:53], v[142:145], v[174:177], v[50:53]
	v_mfma_f32_16x16x32_bf16 v[46:49], v[134:137], v[186:189], v[46:49]
	v_mfma_f32_16x16x32_bf16 v[42:45], v[142:145], v[186:189], v[42:45]
	v_mfma_f32_16x16x32_bf16 v[38:41], v[134:137], v[190:193], v[38:41]
	v_mfma_f32_16x16x32_bf16 v[34:37], v[142:145], v[190:193], v[34:37]
	v_mfma_f32_16x16x32_bf16 v[30:33], v[146:149], v[162:165], v[30:33]
	v_mfma_f32_16x16x32_bf16 v[26:29], v[154:157], v[162:165], v[26:29]
	v_mfma_f32_16x16x32_bf16 v[22:25], v[146:149], v[166:169], v[22:25]
	v_mfma_f32_16x16x32_bf16 v[18:21], v[154:157], v[166:169], v[18:21]
	v_mfma_f32_16x16x32_bf16 v[14:17], v[146:149], v[178:181], v[14:17]
	v_mfma_f32_16x16x32_bf16 v[10:13], v[154:157], v[178:181], v[10:13]
	v_mfma_f32_16x16x32_bf16 v[6:9], v[146:149], v[182:185], v[6:9]
	v_mfma_f32_16x16x32_bf16 v[2:5], v[154:157], v[182:185], v[2:5]
	v_mfma_f32_16x16x32_bf16 v[30:33], v[150:153], v[170:173], v[30:33]
	v_mfma_f32_16x16x32_bf16 v[26:29], v[158:161], v[170:173], v[26:29]
	v_mfma_f32_16x16x32_bf16 v[22:25], v[150:153], v[174:177], v[22:25]
	v_mfma_f32_16x16x32_bf16 v[18:21], v[158:161], v[174:177], v[18:21]
	v_mfma_f32_16x16x32_bf16 v[14:17], v[150:153], v[186:189], v[14:17]
	v_mfma_f32_16x16x32_bf16 v[10:13], v[158:161], v[186:189], v[10:13]
	v_mfma_f32_16x16x32_bf16 v[6:9], v[150:153], v[190:193], v[6:9]
	v_mfma_f32_16x16x32_bf16 v[2:5], v[158:161], v[190:193], v[2:5]
	s_barrier
	s_setprio 0
	s_add_i32 s4, s78, 2
	s_addk_i32 s62, 0x100
	s_addk_i32 s61, 0x100
	s_cmp_ge_u32 s78, s63
	s_mov_b32 s78, s4
	s_cbranch_scc0 .LBB0_546
	s_and_b64 vcc, exec, s[12:13]
	s_cbranch_vccz .LBB0_549
	s_barrier

.LBB0_841:
	ds_read_b128 v[130:133], v240
	ds_read_b128 v[134:137], v241
	ds_read_b128 v[138:141], v242
	ds_read_b128 v[142:145], v243
	ds_read_b128 v[146:149], v244
	ds_read_b128 v[150:153], v245
	ds_read_b128 v[154:157], v246
	ds_read_b128 v[158:161], v247
	s_add_i32 s8, s42, s5
	s_add_i32 s19, s34, s5
	s_add_i32 s18, s8, 0x800
	s_addk_i32 s19, 0x800
	s_cmp_eq_u32 s5, 0
	s_cselect_b32 s20, s0, s18
	s_cselect_b32 s19, s1, s19
	s_add_i32 s18, s20, 0x80
	s_add_i32 s21, s8, 0x40780
	s_mov_b32 s8, s70
	s_mov_b32 m0, s52
	ds_read_b128 v[162:165], v248
	ds_read_b128 v[166:169], v248 offset:2048
	ds_read_b128 v[170:173], v249
	ds_read_b128 v[174:177], v249 offset:2048
	ds_read_b128 v[178:181], v248 offset:4096
	ds_read_b128 v[182:185], v248 offset:6144
	ds_read_b128 v[186:189], v249 offset:4096
	ds_read_b128 v[190:193], v249 offset:6144
	buffer_load_dwordx4 v1, s[8:11], s21 offen lds
	s_mov_b32 m0, s53
	s_nop 0
	buffer_load_dwordx4 v234, s[8:11], s21 offen lds
	s_waitcnt vmcnt(8)
	s_waitcnt lgkmcnt(0)
	v_mfma_f32_16x16x32_bf16 v[74:77], v[130:133], v[162:165], v[74:77]
	v_mfma_f32_16x16x32_bf16 v[70:73], v[138:141], v[162:165], v[70:73]
	v_mfma_f32_16x16x32_bf16 v[66:69], v[130:133], v[166:169], v[66:69]
	v_mfma_f32_16x16x32_bf16 v[82:85], v[138:141], v[166:169], v[82:85]
	s_setprio 1
	s_barrier
	v_mfma_f32_16x16x32_bf16 v[78:81], v[130:133], v[178:181], v[78:81]
	v_mfma_f32_16x16x32_bf16 v[90:93], v[138:141], v[178:181], v[90:93]
	v_mfma_f32_16x16x32_bf16 v[86:89], v[130:133], v[182:185], v[86:89]
	v_mfma_f32_16x16x32_bf16 v[102:105], v[138:141], v[182:185], v[102:105]
	v_mfma_f32_16x16x32_bf16 v[74:77], v[134:137], v[170:173], v[74:77]
	v_mfma_f32_16x16x32_bf16 v[70:73], v[142:145], v[170:173], v[70:73]
	v_mfma_f32_16x16x32_bf16 v[66:69], v[134:137], v[174:177], v[66:69]
	v_mfma_f32_16x16x32_bf16 v[82:85], v[142:145], v[174:177], v[82:85]
	v_mfma_f32_16x16x32_bf16 v[78:81], v[134:137], v[186:189], v[78:81]
	v_mfma_f32_16x16x32_bf16 v[90:93], v[142:145], v[186:189], v[90:93]
	v_mfma_f32_16x16x32_bf16 v[86:89], v[134:137], v[190:193], v[86:89]
	v_mfma_f32_16x16x32_bf16 v[102:105], v[142:145], v[190:193], v[102:105]
	v_mfma_f32_16x16x32_bf16 v[98:101], v[146:149], v[162:165], v[98:101]
	v_mfma_f32_16x16x32_bf16 v[94:97], v[154:157], v[162:165], v[94:97]
	v_mfma_f32_16x16x32_bf16 v[106:109], v[146:149], v[166:169], v[106:109]
	v_mfma_f32_16x16x32_bf16 v[110:113], v[154:157], v[166:169], v[110:113]
	v_mfma_f32_16x16x32_bf16 v[114:117], v[146:149], v[178:181], v[114:117]
	v_mfma_f32_16x16x32_bf16 v[118:121], v[154:157], v[178:181], v[118:121]
	v_mfma_f32_16x16x32_bf16 v[122:125], v[146:149], v[182:185], v[122:125]
	v_mfma_f32_16x16x32_bf16 v[126:129], v[154:157], v[182:185], v[126:129]
	v_mfma_f32_16x16x32_bf16 v[98:101], v[150:153], v[170:173], v[98:101]
	v_mfma_f32_16x16x32_bf16 v[94:97], v[158:161], v[170:173], v[94:97]
	v_mfma_f32_16x16x32_bf16 v[106:109], v[150:153], v[174:177], v[106:109]
	v_mfma_f32_16x16x32_bf16 v[110:113], v[158:161], v[174:177], v[110:113]
	v_mfma_f32_16x16x32_bf16 v[114:117], v[150:153], v[186:189], v[114:117]
	v_mfma_f32_16x16x32_bf16 v[118:121], v[158:161], v[186:189], v[118:121]
	v_mfma_f32_16x16x32_bf16 v[122:125], v[150:153], v[190:193], v[122:125]
	v_mfma_f32_16x16x32_bf16 v[126:129], v[158:161], v[190:193], v[126:129]
	s_barrier
	s_setprio 0
	s_mov_b32 m0, s29
	ds_read_b128 v[162:165], v248 offset:16384
	ds_read_b128 v[166:169], v248 offset:18432
	ds_read_b128 v[170:173], v249 offset:16384
	ds_read_b128 v[174:177], v249 offset:18432
	ds_read_b128 v[178:181], v248 offset:20480
	ds_read_b128 v[182:185], v248 offset:22528
	ds_read_b128 v[186:189], v249 offset:20480
	ds_read_b128 v[190:193], v249 offset:22528
	buffer_load_dwordx4 v233, s[8:11], s19 offen lds
	s_mov_b32 m0, s30
	s_add_i32 s21, s19, 0x40000
	buffer_load_dwordx4 v235, s[8:11], s19 offen lds
	s_mov_b32 m0, s31
	s_nop 0
	buffer_load_dwordx4 v233, s[8:11], s21 offen lds
	s_mov_b32 m0, s35
	s_nop 0
	buffer_load_dwordx4 v235, s[8:11], s21 offen lds
	s_mov_b32 m0, s28
	s_nop 0
	buffer_load_dwordx4 v1, s[8:11], s20 offen lds
	s_mov_b32 m0, s38
	s_nop 0
	buffer_load_dwordx4 v234, s[8:11], s20 offen lds
	s_waitcnt vmcnt(8)
	s_waitcnt lgkmcnt(0)
	s_setprio 1
	s_barrier
	v_mfma_f32_16x16x32_bf16 v[10:13], v[130:133], v[162:165], v[10:13]
	v_mfma_f32_16x16x32_bf16 v[6:9], v[138:141], v[162:165], v[6:9]
	v_mfma_f32_16x16x32_bf16 v[2:5], v[130:133], v[166:169], v[2:5]
	v_mfma_f32_16x16x32_bf16 v[18:21], v[138:141], v[166:169], v[18:21]
	v_mfma_f32_16x16x32_bf16 v[14:17], v[130:133], v[178:181], v[14:17]
	v_mfma_f32_16x16x32_bf16 v[26:29], v[138:141], v[178:181], v[26:29]
	v_mfma_f32_16x16x32_bf16 v[22:25], v[130:133], v[182:185], v[22:25]
	v_mfma_f32_16x16x32_bf16 v[38:41], v[138:141], v[182:185], v[38:41]
	v_mfma_f32_16x16x32_bf16 v[10:13], v[134:137], v[170:173], v[10:13]
	v_mfma_f32_16x16x32_bf16 v[6:9], v[142:145], v[170:173], v[6:9]
	v_mfma_f32_16x16x32_bf16 v[2:5], v[134:137], v[174:177], v[2:5]
	v_mfma_f32_16x16x32_bf16 v[18:21], v[142:145], v[174:177], v[18:21]
	v_mfma_f32_16x16x32_bf16 v[14:17], v[134:137], v[186:189], v[14:17]
	v_mfma_f32_16x16x32_bf16 v[26:29], v[142:145], v[186:189], v[26:29]
	v_mfma_f32_16x16x32_bf16 v[22:25], v[134:137], v[190:193], v[22:25]
	v_mfma_f32_16x16x32_bf16 v[38:41], v[142:145], v[190:193], v[38:41]
	v_mfma_f32_16x16x32_bf16 v[34:37], v[146:149], v[162:165], v[34:37]
	v_mfma_f32_16x16x32_bf16 v[30:33], v[154:157], v[162:165], v[30:33]
	v_mfma_f32_16x16x32_bf16 v[42:45], v[146:149], v[166:169], v[42:45]
	v_mfma_f32_16x16x32_bf16 v[46:49], v[154:157], v[166:169], v[46:49]
	v_mfma_f32_16x16x32_bf16 v[50:53], v[146:149], v[178:181], v[50:53]
	v_mfma_f32_16x16x32_bf16 v[54:57], v[154:157], v[178:181], v[54:57]
	v_mfma_f32_16x16x32_bf16 v[58:61], v[146:149], v[182:185], v[58:61]
	v_mfma_f32_16x16x32_bf16 v[62:65], v[154:157], v[182:185], v[62:65]
	v_mfma_f32_16x16x32_bf16 v[34:37], v[150:153], v[170:173], v[34:37]
	v_mfma_f32_16x16x32_bf16 v[30:33], v[158:161], v[170:173], v[30:33]
	v_mfma_f32_16x16x32_bf16 v[42:45], v[150:153], v[174:177], v[42:45]
	v_mfma_f32_16x16x32_bf16 v[46:49], v[158:161], v[174:177], v[46:49]
	v_mfma_f32_16x16x32_bf16 v[50:53], v[150:153], v[186:189], v[50:53]
	v_mfma_f32_16x16x32_bf16 v[54:57], v[158:161], v[186:189], v[54:57]
	v_mfma_f32_16x16x32_bf16 v[58:61], v[150:153], v[190:193], v[58:61]
	v_mfma_f32_16x16x32_bf16 v[62:65], v[158:161], v[190:193], v[62:65]
	s_barrier
	s_setprio 0
	ds_read_b128 v[130:133], v194
	ds_read_b128 v[134:137], v195
	ds_read_b128 v[138:141], v196
	ds_read_b128 v[142:145], v197
	ds_read_b128 v[146:149], v198
	ds_read_b128 v[150:153], v199
	ds_read_b128 v[154:157], v200
	ds_read_b128 v[158:161], v201
	s_add_i32 s20, s20, 0x40000
	s_mov_b32 m0, s39
	ds_read_b128 v[162:165], v248 offset:32768
	ds_read_b128 v[166:169], v248 offset:34816
	ds_read_b128 v[170:173], v249 offset:32768
	ds_read_b128 v[174:177], v249 offset:34816
	ds_read_b128 v[178:181], v248 offset:36864
	ds_read_b128 v[182:185], v248 offset:38912
	ds_read_b128 v[186:189], v249 offset:36864
	ds_read_b128 v[190:193], v249 offset:38912
	buffer_load_dwordx4 v1, s[8:11], s20 offen lds
	s_mov_b32 m0, s41
	s_nop 0
	buffer_load_dwordx4 v234, s[8:11], s20 offen lds
	s_waitcnt vmcnt(8)
	s_waitcnt lgkmcnt(0)
	v_mfma_f32_16x16x32_bf16 v[74:77], v[130:133], v[162:165], v[74:77]
	v_mfma_f32_16x16x32_bf16 v[70:73], v[138:141], v[162:165], v[70:73]
	v_mfma_f32_16x16x32_bf16 v[66:69], v[130:133], v[166:169], v[66:69]
	v_mfma_f32_16x16x32_bf16 v[82:85], v[138:141], v[166:169], v[82:85]
	s_setprio 1
	s_barrier
	v_mfma_f32_16x16x32_bf16 v[78:81], v[130:133], v[178:181], v[78:81]
	v_mfma_f32_16x16x32_bf16 v[90:93], v[138:141], v[178:181], v[90:93]
	v_mfma_f32_16x16x32_bf16 v[86:89], v[130:133], v[182:185], v[86:89]
	v_mfma_f32_16x16x32_bf16 v[102:105], v[138:141], v[182:185], v[102:105]
	v_mfma_f32_16x16x32_bf16 v[74:77], v[134:137], v[170:173], v[74:77]
	v_mfma_f32_16x16x32_bf16 v[70:73], v[142:145], v[170:173], v[70:73]
	v_mfma_f32_16x16x32_bf16 v[66:69], v[134:137], v[174:177], v[66:69]
	v_mfma_f32_16x16x32_bf16 v[82:85], v[142:145], v[174:177], v[82:85]
	v_mfma_f32_16x16x32_bf16 v[78:81], v[134:137], v[186:189], v[78:81]
	v_mfma_f32_16x16x32_bf16 v[90:93], v[142:145], v[186:189], v[90:93]
	v_mfma_f32_16x16x32_bf16 v[86:89], v[134:137], v[190:193], v[86:89]
	v_mfma_f32_16x16x32_bf16 v[102:105], v[142:145], v[190:193], v[102:105]
	v_mfma_f32_16x16x32_bf16 v[98:101], v[146:149], v[162:165], v[98:101]
	v_mfma_f32_16x16x32_bf16 v[94:97], v[154:157], v[162:165], v[94:97]
	v_mfma_f32_16x16x32_bf16 v[106:109], v[146:149], v[166:169], v[106:109]
	v_mfma_f32_16x16x32_bf16 v[110:113], v[154:157], v[166:169], v[110:113]
	v_mfma_f32_16x16x32_bf16 v[114:117], v[146:149], v[178:181], v[114:117]
	v_mfma_f32_16x16x32_bf16 v[118:121], v[154:157], v[178:181], v[118:121]
	v_mfma_f32_16x16x32_bf16 v[122:125], v[146:149], v[182:185], v[122:125]
	v_mfma_f32_16x16x32_bf16 v[126:129], v[154:157], v[182:185], v[126:129]
	v_mfma_f32_16x16x32_bf16 v[98:101], v[150:153], v[170:173], v[98:101]
	v_mfma_f32_16x16x32_bf16 v[94:97], v[158:161], v[170:173], v[94:97]
	v_mfma_f32_16x16x32_bf16 v[106:109], v[150:153], v[174:177], v[106:109]
	v_mfma_f32_16x16x32_bf16 v[110:113], v[158:161], v[174:177], v[110:113]
	v_mfma_f32_16x16x32_bf16 v[114:117], v[150:153], v[186:189], v[114:117]
	v_mfma_f32_16x16x32_bf16 v[118:121], v[158:161], v[186:189], v[118:121]
	v_mfma_f32_16x16x32_bf16 v[122:125], v[150:153], v[190:193], v[122:125]
	v_mfma_f32_16x16x32_bf16 v[126:129], v[158:161], v[190:193], v[126:129]
	s_barrier
	s_setprio 0
	s_mov_b32 m0, s44
	s_add_i32 s20, s19, 0x80
	ds_read_b128 v[162:165], v248 offset:49152
	ds_read_b128 v[166:169], v248 offset:51200
	ds_read_b128 v[170:173], v249 offset:49152
	ds_read_b128 v[174:177], v249 offset:51200
	ds_read_b128 v[178:181], v248 offset:53248
	ds_read_b128 v[182:185], v248 offset:55296
	ds_read_b128 v[186:189], v249 offset:53248
	ds_read_b128 v[190:193], v249 offset:55296
	buffer_load_dwordx4 v233, s[8:11], s20 offen lds
	s_mov_b32 m0, s45
	s_add_i32 s19, s19, 0x40080
	buffer_load_dwordx4 v235, s[8:11], s20 offen lds
	s_mov_b32 m0, s48
	s_nop 0
	buffer_load_dwordx4 v233, s[8:11], s19 offen lds
	s_mov_b32 m0, s49
	s_nop 0
	buffer_load_dwordx4 v235, s[8:11], s19 offen lds
	s_mov_b32 m0, s46
	s_nop 0
	buffer_load_dwordx4 v1, s[8:11], s18 offen lds
	s_mov_b32 m0, s47
	s_nop 0
	buffer_load_dwordx4 v234, s[8:11], s18 offen lds
	s_waitcnt vmcnt(8)
	s_waitcnt lgkmcnt(0)
	s_setprio 1
	s_barrier
	v_mfma_f32_16x16x32_bf16 v[10:13], v[130:133], v[162:165], v[10:13]
	v_mfma_f32_16x16x32_bf16 v[6:9], v[138:141], v[162:165], v[6:9]
	v_mfma_f32_16x16x32_bf16 v[2:5], v[130:133], v[166:169], v[2:5]
	v_mfma_f32_16x16x32_bf16 v[18:21], v[138:141], v[166:169], v[18:21]
	v_mfma_f32_16x16x32_bf16 v[14:17], v[130:133], v[178:181], v[14:17]
	v_mfma_f32_16x16x32_bf16 v[26:29], v[138:141], v[178:181], v[26:29]
	v_mfma_f32_16x16x32_bf16 v[22:25], v[130:133], v[182:185], v[22:25]
	v_mfma_f32_16x16x32_bf16 v[38:41], v[138:141], v[182:185], v[38:41]
	v_mfma_f32_16x16x32_bf16 v[10:13], v[134:137], v[170:173], v[10:13]
	v_mfma_f32_16x16x32_bf16 v[6:9], v[142:145], v[170:173], v[6:9]
	v_mfma_f32_16x16x32_bf16 v[2:5], v[134:137], v[174:177], v[2:5]
	v_mfma_f32_16x16x32_bf16 v[18:21], v[142:145], v[174:177], v[18:21]
	v_mfma_f32_16x16x32_bf16 v[14:17], v[134:137], v[186:189], v[14:17]
	v_mfma_f32_16x16x32_bf16 v[26:29], v[142:145], v[186:189], v[26:29]
	v_mfma_f32_16x16x32_bf16 v[22:25], v[134:137], v[190:193], v[22:25]
	v_mfma_f32_16x16x32_bf16 v[38:41], v[142:145], v[190:193], v[38:41]
	v_mfma_f32_16x16x32_bf16 v[34:37], v[146:149], v[162:165], v[34:37]
	v_mfma_f32_16x16x32_bf16 v[30:33], v[154:157], v[162:165], v[30:33]
	v_mfma_f32_16x16x32_bf16 v[42:45], v[146:149], v[166:169], v[42:45]
	v_mfma_f32_16x16x32_bf16 v[46:49], v[154:157], v[166:169], v[46:49]
	v_mfma_f32_16x16x32_bf16 v[50:53], v[146:149], v[178:181], v[50:53]
	v_mfma_f32_16x16x32_bf16 v[54:57], v[154:157], v[178:181], v[54:57]
	v_mfma_f32_16x16x32_bf16 v[58:61], v[146:149], v[182:185], v[58:61]
	v_mfma_f32_16x16x32_bf16 v[62:65], v[154:157], v[182:185], v[62:65]
	v_mfma_f32_16x16x32_bf16 v[34:37], v[150:153], v[170:173], v[34:37]
	v_mfma_f32_16x16x32_bf16 v[30:33], v[158:161], v[170:173], v[30:33]
	v_mfma_f32_16x16x32_bf16 v[42:45], v[150:153], v[174:177], v[42:45]
	v_mfma_f32_16x16x32_bf16 v[46:49], v[158:161], v[174:177], v[46:49]
	v_mfma_f32_16x16x32_bf16 v[50:53], v[150:153], v[186:189], v[50:53]
	v_mfma_f32_16x16x32_bf16 v[54:57], v[158:161], v[186:189], v[54:57]
	v_mfma_f32_16x16x32_bf16 v[58:61], v[150:153], v[190:193], v[58:61]
	v_mfma_f32_16x16x32_bf16 v[62:65], v[158:161], v[190:193], v[62:65]
	s_barrier
	s_setprio 0
	s_add_i32 s4, s4, 2
	s_addk_i32 s5, 0x100
	s_cmp_gt_u32 s4, 13
	s_cbranch_scc0 .LBB0_841
	s_and_b64 vcc, exec, s[16:17]
	s_cbranch_vccz .LBB0_844
	s_barrier

.LBB0_1122:
	ds_read_b128 v[130:133], v240
	ds_read_b128 v[134:137], v241
	ds_read_b128 v[138:141], v242
	ds_read_b128 v[142:145], v243
	ds_read_b128 v[146:149], v244
	ds_read_b128 v[150:153], v245
	ds_read_b128 v[154:157], v246
	ds_read_b128 v[158:161], v247
	s_add_i32 s8, s31, s53
	s_add_i32 s55, s26, s53
	s_add_i32 s54, s8, 0x800
	s_addk_i32 s55, 0x800
	s_cmp_eq_u32 s53, 0
	s_cselect_b32 s56, s4, s54
	s_cselect_b32 s55, s5, s55
	s_add_i32 s54, s56, 0x80
	s_add_i32 s57, s8, 0x40780
	s_mov_b32 s8, s70
	s_mov_b32 m0, s44
	ds_read_b128 v[162:165], v248
	ds_read_b128 v[166:169], v248 offset:2048
	ds_read_b128 v[170:173], v249
	ds_read_b128 v[174:177], v249 offset:2048
	ds_read_b128 v[178:181], v248 offset:4096
	ds_read_b128 v[182:185], v248 offset:6144
	ds_read_b128 v[186:189], v249 offset:4096
	ds_read_b128 v[190:193], v249 offset:6144
	buffer_load_dwordx4 v1, s[8:11], s57 offen lds
	s_mov_b32 m0, s45
	s_nop 0
	buffer_load_dwordx4 v234, s[8:11], s57 offen lds
	s_waitcnt vmcnt(8)
	s_waitcnt lgkmcnt(0)
	v_mfma_f32_16x16x32_bf16 v[126:129], v[130:133], v[162:165], v[126:129]
	v_mfma_f32_16x16x32_bf16 v[122:125], v[138:141], v[162:165], v[122:125]
	v_mfma_f32_16x16x32_bf16 v[118:121], v[130:133], v[166:169], v[118:121]
	v_mfma_f32_16x16x32_bf16 v[114:117], v[138:141], v[166:169], v[114:117]
	s_setprio 1
	s_barrier
	v_mfma_f32_16x16x32_bf16 v[110:113], v[130:133], v[178:181], v[110:113]
	v_mfma_f32_16x16x32_bf16 v[106:109], v[138:141], v[178:181], v[106:109]
	v_mfma_f32_16x16x32_bf16 v[102:105], v[130:133], v[182:185], v[102:105]
	v_mfma_f32_16x16x32_bf16 v[98:101], v[138:141], v[182:185], v[98:101]
	v_mfma_f32_16x16x32_bf16 v[126:129], v[134:137], v[170:173], v[126:129]
	v_mfma_f32_16x16x32_bf16 v[122:125], v[142:145], v[170:173], v[122:125]
	v_mfma_f32_16x16x32_bf16 v[118:121], v[134:137], v[174:177], v[118:121]
	v_mfma_f32_16x16x32_bf16 v[114:117], v[142:145], v[174:177], v[114:117]
	v_mfma_f32_16x16x32_bf16 v[110:113], v[134:137], v[186:189], v[110:113]
	v_mfma_f32_16x16x32_bf16 v[106:109], v[142:145], v[186:189], v[106:109]
	v_mfma_f32_16x16x32_bf16 v[102:105], v[134:137], v[190:193], v[102:105]
	v_mfma_f32_16x16x32_bf16 v[98:101], v[142:145], v[190:193], v[98:101]
	v_mfma_f32_16x16x32_bf16 v[94:97], v[146:149], v[162:165], v[94:97]
	v_mfma_f32_16x16x32_bf16 v[90:93], v[154:157], v[162:165], v[90:93]
	v_mfma_f32_16x16x32_bf16 v[86:89], v[146:149], v[166:169], v[86:89]
	v_mfma_f32_16x16x32_bf16 v[82:85], v[154:157], v[166:169], v[82:85]
	v_mfma_f32_16x16x32_bf16 v[78:81], v[146:149], v[178:181], v[78:81]
	v_mfma_f32_16x16x32_bf16 v[74:77], v[154:157], v[178:181], v[74:77]
	v_mfma_f32_16x16x32_bf16 v[70:73], v[146:149], v[182:185], v[70:73]
	v_mfma_f32_16x16x32_bf16 v[66:69], v[154:157], v[182:185], v[66:69]
	v_mfma_f32_16x16x32_bf16 v[94:97], v[150:153], v[170:173], v[94:97]
	v_mfma_f32_16x16x32_bf16 v[90:93], v[158:161], v[170:173], v[90:93]
	v_mfma_f32_16x16x32_bf16 v[86:89], v[150:153], v[174:177], v[86:89]
	v_mfma_f32_16x16x32_bf16 v[82:85], v[158:161], v[174:177], v[82:85]
	v_mfma_f32_16x16x32_bf16 v[78:81], v[150:153], v[186:189], v[78:81]
	v_mfma_f32_16x16x32_bf16 v[74:77], v[158:161], v[186:189], v[74:77]
	v_mfma_f32_16x16x32_bf16 v[70:73], v[150:153], v[190:193], v[70:73]
	v_mfma_f32_16x16x32_bf16 v[66:69], v[158:161], v[190:193], v[66:69]
	s_barrier
	s_setprio 0
	s_mov_b32 m0, s23
	ds_read_b128 v[162:165], v248 offset:16384
	ds_read_b128 v[166:169], v248 offset:18432
	ds_read_b128 v[170:173], v249 offset:16384
	ds_read_b128 v[174:177], v249 offset:18432
	ds_read_b128 v[178:181], v248 offset:20480
	ds_read_b128 v[182:185], v248 offset:22528
	ds_read_b128 v[186:189], v249 offset:20480
	ds_read_b128 v[190:193], v249 offset:22528
	buffer_load_dwordx4 v233, s[8:11], s55 offen lds
	s_mov_b32 m0, s24
	s_add_i32 s57, s55, 0x40000
	buffer_load_dwordx4 v235, s[8:11], s55 offen lds
	s_mov_b32 m0, s25
	s_nop 0
	buffer_load_dwordx4 v233, s[8:11], s57 offen lds
	s_mov_b32 m0, s27
	s_nop 0
	buffer_load_dwordx4 v235, s[8:11], s57 offen lds
	s_mov_b32 m0, s22
	s_nop 0
	buffer_load_dwordx4 v1, s[8:11], s56 offen lds
	s_mov_b32 m0, s28
	s_nop 0
	buffer_load_dwordx4 v234, s[8:11], s56 offen lds
	s_waitcnt vmcnt(8)
	s_waitcnt lgkmcnt(0)
	s_setprio 1
	s_barrier
	v_mfma_f32_16x16x32_bf16 v[62:65], v[130:133], v[162:165], v[62:65]
	v_mfma_f32_16x16x32_bf16 v[58:61], v[138:141], v[162:165], v[58:61]
	v_mfma_f32_16x16x32_bf16 v[54:57], v[130:133], v[166:169], v[54:57]
	v_mfma_f32_16x16x32_bf16 v[50:53], v[138:141], v[166:169], v[50:53]
	v_mfma_f32_16x16x32_bf16 v[46:49], v[130:133], v[178:181], v[46:49]
	v_mfma_f32_16x16x32_bf16 v[42:45], v[138:141], v[178:181], v[42:45]
	v_mfma_f32_16x16x32_bf16 v[38:41], v[130:133], v[182:185], v[38:41]
	v_mfma_f32_16x16x32_bf16 v[34:37], v[138:141], v[182:185], v[34:37]
	v_mfma_f32_16x16x32_bf16 v[62:65], v[134:137], v[170:173], v[62:65]
	v_mfma_f32_16x16x32_bf16 v[58:61], v[142:145], v[170:173], v[58:61]
	v_mfma_f32_16x16x32_bf16 v[54:57], v[134:137], v[174:177], v[54:57]
	v_mfma_f32_16x16x32_bf16 v[50:53], v[142:145], v[174:177], v[50:53]
	v_mfma_f32_16x16x32_bf16 v[46:49], v[134:137], v[186:189], v[46:49]
	v_mfma_f32_16x16x32_bf16 v[42:45], v[142:145], v[186:189], v[42:45]
	v_mfma_f32_16x16x32_bf16 v[38:41], v[134:137], v[190:193], v[38:41]
	v_mfma_f32_16x16x32_bf16 v[34:37], v[142:145], v[190:193], v[34:37]
	v_mfma_f32_16x16x32_bf16 v[30:33], v[146:149], v[162:165], v[30:33]
	v_mfma_f32_16x16x32_bf16 v[26:29], v[154:157], v[162:165], v[26:29]
	v_mfma_f32_16x16x32_bf16 v[22:25], v[146:149], v[166:169], v[22:25]
	v_mfma_f32_16x16x32_bf16 v[18:21], v[154:157], v[166:169], v[18:21]
	v_mfma_f32_16x16x32_bf16 v[14:17], v[146:149], v[178:181], v[14:17]
	v_mfma_f32_16x16x32_bf16 v[10:13], v[154:157], v[178:181], v[10:13]
	v_mfma_f32_16x16x32_bf16 v[6:9], v[146:149], v[182:185], v[6:9]
	v_mfma_f32_16x16x32_bf16 v[2:5], v[154:157], v[182:185], v[2:5]
	v_mfma_f32_16x16x32_bf16 v[30:33], v[150:153], v[170:173], v[30:33]
	v_mfma_f32_16x16x32_bf16 v[26:29], v[158:161], v[170:173], v[26:29]
	v_mfma_f32_16x16x32_bf16 v[22:25], v[150:153], v[174:177], v[22:25]
	v_mfma_f32_16x16x32_bf16 v[18:21], v[158:161], v[174:177], v[18:21]
	v_mfma_f32_16x16x32_bf16 v[14:17], v[150:153], v[186:189], v[14:17]
	v_mfma_f32_16x16x32_bf16 v[10:13], v[158:161], v[186:189], v[10:13]
	v_mfma_f32_16x16x32_bf16 v[6:9], v[150:153], v[190:193], v[6:9]
	v_mfma_f32_16x16x32_bf16 v[2:5], v[158:161], v[190:193], v[2:5]
	s_barrier
	s_setprio 0
	ds_read_b128 v[130:133], v194
	ds_read_b128 v[134:137], v195
	ds_read_b128 v[138:141], v196
	ds_read_b128 v[142:145], v197
	ds_read_b128 v[146:149], v198
	ds_read_b128 v[150:153], v199
	ds_read_b128 v[154:157], v200
	ds_read_b128 v[158:161], v201
	s_add_i32 s56, s56, 0x40000
	s_mov_b32 m0, s29
	ds_read_b128 v[162:165], v248 offset:32768
	ds_read_b128 v[166:169], v248 offset:34816
	ds_read_b128 v[170:173], v249 offset:32768
	ds_read_b128 v[174:177], v249 offset:34816
	ds_read_b128 v[178:181], v248 offset:36864
	ds_read_b128 v[182:185], v248 offset:38912
	ds_read_b128 v[186:189], v249 offset:36864
	ds_read_b128 v[190:193], v249 offset:38912
	buffer_load_dwordx4 v1, s[8:11], s56 offen lds
	s_mov_b32 m0, s30
	s_nop 0
	buffer_load_dwordx4 v234, s[8:11], s56 offen lds
	s_waitcnt vmcnt(8)
	s_waitcnt lgkmcnt(0)
	v_mfma_f32_16x16x32_bf16 v[126:129], v[130:133], v[162:165], v[126:129]
	v_mfma_f32_16x16x32_bf16 v[122:125], v[138:141], v[162:165], v[122:125]
	v_mfma_f32_16x16x32_bf16 v[118:121], v[130:133], v[166:169], v[118:121]
	v_mfma_f32_16x16x32_bf16 v[114:117], v[138:141], v[166:169], v[114:117]
	s_setprio 1
	s_barrier
	v_mfma_f32_16x16x32_bf16 v[110:113], v[130:133], v[178:181], v[110:113]
	v_mfma_f32_16x16x32_bf16 v[106:109], v[138:141], v[178:181], v[106:109]
	v_mfma_f32_16x16x32_bf16 v[102:105], v[130:133], v[182:185], v[102:105]
	v_mfma_f32_16x16x32_bf16 v[98:101], v[138:141], v[182:185], v[98:101]
	v_mfma_f32_16x16x32_bf16 v[126:129], v[134:137], v[170:173], v[126:129]
	v_mfma_f32_16x16x32_bf16 v[122:125], v[142:145], v[170:173], v[122:125]
	v_mfma_f32_16x16x32_bf16 v[118:121], v[134:137], v[174:177], v[118:121]
	v_mfma_f32_16x16x32_bf16 v[114:117], v[142:145], v[174:177], v[114:117]
	v_mfma_f32_16x16x32_bf16 v[110:113], v[134:137], v[186:189], v[110:113]
	v_mfma_f32_16x16x32_bf16 v[106:109], v[142:145], v[186:189], v[106:109]
	v_mfma_f32_16x16x32_bf16 v[102:105], v[134:137], v[190:193], v[102:105]
	v_mfma_f32_16x16x32_bf16 v[98:101], v[142:145], v[190:193], v[98:101]
	v_mfma_f32_16x16x32_bf16 v[94:97], v[146:149], v[162:165], v[94:97]
	v_mfma_f32_16x16x32_bf16 v[90:93], v[154:157], v[162:165], v[90:93]
	v_mfma_f32_16x16x32_bf16 v[86:89], v[146:149], v[166:169], v[86:89]
	v_mfma_f32_16x16x32_bf16 v[82:85], v[154:157], v[166:169], v[82:85]
	v_mfma_f32_16x16x32_bf16 v[78:81], v[146:149], v[178:181], v[78:81]
	v_mfma_f32_16x16x32_bf16 v[74:77], v[154:157], v[178:181], v[74:77]
	v_mfma_f32_16x16x32_bf16 v[70:73], v[146:149], v[182:185], v[70:73]
	v_mfma_f32_16x16x32_bf16 v[66:69], v[154:157], v[182:185], v[66:69]
	v_mfma_f32_16x16x32_bf16 v[94:97], v[150:153], v[170:173], v[94:97]
	v_mfma_f32_16x16x32_bf16 v[90:93], v[158:161], v[170:173], v[90:93]
	v_mfma_f32_16x16x32_bf16 v[86:89], v[150:153], v[174:177], v[86:89]
	v_mfma_f32_16x16x32_bf16 v[82:85], v[158:161], v[174:177], v[82:85]
	v_mfma_f32_16x16x32_bf16 v[78:81], v[150:153], v[186:189], v[78:81]
	v_mfma_f32_16x16x32_bf16 v[74:77], v[158:161], v[186:189], v[74:77]
	v_mfma_f32_16x16x32_bf16 v[70:73], v[150:153], v[190:193], v[70:73]
	v_mfma_f32_16x16x32_bf16 v[66:69], v[158:161], v[190:193], v[66:69]
	s_barrier
	s_setprio 0
	s_mov_b32 m0, s35
	s_add_i32 s56, s55, 0x80
	ds_read_b128 v[162:165], v248 offset:49152
	ds_read_b128 v[166:169], v248 offset:51200
	ds_read_b128 v[170:173], v249 offset:49152
	ds_read_b128 v[174:177], v249 offset:51200
	ds_read_b128 v[178:181], v248 offset:53248
	ds_read_b128 v[182:185], v248 offset:55296
	ds_read_b128 v[186:189], v249 offset:53248
	ds_read_b128 v[190:193], v249 offset:55296
	buffer_load_dwordx4 v233, s[8:11], s56 offen lds
	s_mov_b32 m0, s36
	s_add_i32 s55, s55, 0x40080
	buffer_load_dwordx4 v235, s[8:11], s56 offen lds
	s_mov_b32 m0, s39
	s_nop 0
	buffer_load_dwordx4 v233, s[8:11], s55 offen lds
	s_mov_b32 m0, s41
	s_nop 0
	buffer_load_dwordx4 v235, s[8:11], s55 offen lds
	s_mov_b32 m0, s37
	s_nop 0
	buffer_load_dwordx4 v1, s[8:11], s54 offen lds
	s_mov_b32 m0, s38
	s_nop 0
	buffer_load_dwordx4 v234, s[8:11], s54 offen lds
	s_waitcnt vmcnt(8)
	s_waitcnt lgkmcnt(0)
	s_setprio 1
	s_barrier
	v_mfma_f32_16x16x32_bf16 v[62:65], v[130:133], v[162:165], v[62:65]
	v_mfma_f32_16x16x32_bf16 v[58:61], v[138:141], v[162:165], v[58:61]
	v_mfma_f32_16x16x32_bf16 v[54:57], v[130:133], v[166:169], v[54:57]
	v_mfma_f32_16x16x32_bf16 v[50:53], v[138:141], v[166:169], v[50:53]
	v_mfma_f32_16x16x32_bf16 v[46:49], v[130:133], v[178:181], v[46:49]
	v_mfma_f32_16x16x32_bf16 v[42:45], v[138:141], v[178:181], v[42:45]
	v_mfma_f32_16x16x32_bf16 v[38:41], v[130:133], v[182:185], v[38:41]
	v_mfma_f32_16x16x32_bf16 v[34:37], v[138:141], v[182:185], v[34:37]
	v_mfma_f32_16x16x32_bf16 v[62:65], v[134:137], v[170:173], v[62:65]
	v_mfma_f32_16x16x32_bf16 v[58:61], v[142:145], v[170:173], v[58:61]
	v_mfma_f32_16x16x32_bf16 v[54:57], v[134:137], v[174:177], v[54:57]
	v_mfma_f32_16x16x32_bf16 v[50:53], v[142:145], v[174:177], v[50:53]
	v_mfma_f32_16x16x32_bf16 v[46:49], v[134:137], v[186:189], v[46:49]
	v_mfma_f32_16x16x32_bf16 v[42:45], v[142:145], v[186:189], v[42:45]
	v_mfma_f32_16x16x32_bf16 v[38:41], v[134:137], v[190:193], v[38:41]
	v_mfma_f32_16x16x32_bf16 v[34:37], v[142:145], v[190:193], v[34:37]
	v_mfma_f32_16x16x32_bf16 v[30:33], v[146:149], v[162:165], v[30:33]
	v_mfma_f32_16x16x32_bf16 v[26:29], v[154:157], v[162:165], v[26:29]
	v_mfma_f32_16x16x32_bf16 v[22:25], v[146:149], v[166:169], v[22:25]
	v_mfma_f32_16x16x32_bf16 v[18:21], v[154:157], v[166:169], v[18:21]
	v_mfma_f32_16x16x32_bf16 v[14:17], v[146:149], v[178:181], v[14:17]
	v_mfma_f32_16x16x32_bf16 v[10:13], v[154:157], v[178:181], v[10:13]
	v_mfma_f32_16x16x32_bf16 v[6:9], v[146:149], v[182:185], v[6:9]
	v_mfma_f32_16x16x32_bf16 v[2:5], v[154:157], v[182:185], v[2:5]
	v_mfma_f32_16x16x32_bf16 v[30:33], v[150:153], v[170:173], v[30:33]
	v_mfma_f32_16x16x32_bf16 v[26:29], v[158:161], v[170:173], v[26:29]
	v_mfma_f32_16x16x32_bf16 v[22:25], v[150:153], v[174:177], v[22:25]
	v_mfma_f32_16x16x32_bf16 v[18:21], v[158:161], v[174:177], v[18:21]
	v_mfma_f32_16x16x32_bf16 v[14:17], v[150:153], v[186:189], v[14:17]
	v_mfma_f32_16x16x32_bf16 v[10:13], v[158:161], v[186:189], v[10:13]
	v_mfma_f32_16x16x32_bf16 v[6:9], v[150:153], v[190:193], v[6:9]
	v_mfma_f32_16x16x32_bf16 v[2:5], v[158:161], v[190:193], v[2:5]
	s_barrier
	s_setprio 0
	s_add_i32 s33, s33, 2
	s_addk_i32 s53, 0x100
	s_cmp_gt_u32 s33, 13
	s_cbranch_scc0 .LBB0_1122
	s_and_b64 vcc, exec, s[16:17]
	s_cbranch_vccz .LBB0_1125
	s_barrier

.LBB0_1251:
	ds_read_b128 v[130:133], v239
	ds_read_b128 v[134:137], v240
	ds_read_b128 v[138:141], v241
	ds_read_b128 v[142:145], v242
	ds_read_b128 v[146:149], v243
	ds_read_b128 v[150:153], v244
	ds_read_b128 v[154:157], v245
	ds_read_b128 v[158:161], v246
	s_add_i32 s8, s51, s5
	s_add_i32 s31, s46, s5
	s_add_i32 s30, s8, 0x2000
	s_addk_i32 s31, 0x2000
	s_cmp_eq_u32 s5, 0
	s_cselect_b32 s33, s0, s30
	s_cselect_b32 s31, s1, s31
	s_add_i32 s30, s33, 0x80
	s_add_i32 s34, s8, 0x101f80
	s_mov_b32 s8, s70
	s_mov_b32 m0, s61
	ds_read_b128 v[162:165], v247
	ds_read_b128 v[166:169], v247 offset:2048
	ds_read_b128 v[170:173], v248
	ds_read_b128 v[174:177], v248 offset:2048
	ds_read_b128 v[178:181], v247 offset:4096
	ds_read_b128 v[182:185], v247 offset:6144
	ds_read_b128 v[186:189], v248 offset:4096
	ds_read_b128 v[190:193], v248 offset:6144
	buffer_load_dwordx4 v230, s[8:11], s34 offen lds
	s_mov_b32 m0, s64
	s_nop 0
	buffer_load_dwordx4 v233, s[8:11], s34 offen lds
	s_waitcnt vmcnt(8)
	s_waitcnt lgkmcnt(0)
	v_mfma_f32_16x16x32_bf16 v[74:77], v[130:133], v[162:165], v[74:77]
	v_mfma_f32_16x16x32_bf16 v[70:73], v[138:141], v[162:165], v[70:73]
	v_mfma_f32_16x16x32_bf16 v[66:69], v[130:133], v[166:169], v[66:69]
	v_mfma_f32_16x16x32_bf16 v[82:85], v[138:141], v[166:169], v[82:85]
	s_setprio 1
	s_barrier
	v_mfma_f32_16x16x32_bf16 v[78:81], v[130:133], v[178:181], v[78:81]
	v_mfma_f32_16x16x32_bf16 v[90:93], v[138:141], v[178:181], v[90:93]
	v_mfma_f32_16x16x32_bf16 v[86:89], v[130:133], v[182:185], v[86:89]
	v_mfma_f32_16x16x32_bf16 v[102:105], v[138:141], v[182:185], v[102:105]
	v_mfma_f32_16x16x32_bf16 v[74:77], v[134:137], v[170:173], v[74:77]
	v_mfma_f32_16x16x32_bf16 v[70:73], v[142:145], v[170:173], v[70:73]
	v_mfma_f32_16x16x32_bf16 v[66:69], v[134:137], v[174:177], v[66:69]
	v_mfma_f32_16x16x32_bf16 v[82:85], v[142:145], v[174:177], v[82:85]
	v_mfma_f32_16x16x32_bf16 v[78:81], v[134:137], v[186:189], v[78:81]
	v_mfma_f32_16x16x32_bf16 v[90:93], v[142:145], v[186:189], v[90:93]
	v_mfma_f32_16x16x32_bf16 v[86:89], v[134:137], v[190:193], v[86:89]
	v_mfma_f32_16x16x32_bf16 v[102:105], v[142:145], v[190:193], v[102:105]
	v_mfma_f32_16x16x32_bf16 v[98:101], v[146:149], v[162:165], v[98:101]
	v_mfma_f32_16x16x32_bf16 v[94:97], v[154:157], v[162:165], v[94:97]
	v_mfma_f32_16x16x32_bf16 v[106:109], v[146:149], v[166:169], v[106:109]
	v_mfma_f32_16x16x32_bf16 v[110:113], v[154:157], v[166:169], v[110:113]
	v_mfma_f32_16x16x32_bf16 v[114:117], v[146:149], v[178:181], v[114:117]
	v_mfma_f32_16x16x32_bf16 v[118:121], v[154:157], v[178:181], v[118:121]
	v_mfma_f32_16x16x32_bf16 v[122:125], v[146:149], v[182:185], v[122:125]
	v_mfma_f32_16x16x32_bf16 v[126:129], v[154:157], v[182:185], v[126:129]
	v_mfma_f32_16x16x32_bf16 v[98:101], v[150:153], v[170:173], v[98:101]
	v_mfma_f32_16x16x32_bf16 v[94:97], v[158:161], v[170:173], v[94:97]
	v_mfma_f32_16x16x32_bf16 v[106:109], v[150:153], v[174:177], v[106:109]
	v_mfma_f32_16x16x32_bf16 v[110:113], v[158:161], v[174:177], v[110:113]
	v_mfma_f32_16x16x32_bf16 v[114:117], v[150:153], v[186:189], v[114:117]
	v_mfma_f32_16x16x32_bf16 v[118:121], v[158:161], v[186:189], v[118:121]
	v_mfma_f32_16x16x32_bf16 v[122:125], v[150:153], v[190:193], v[122:125]
	v_mfma_f32_16x16x32_bf16 v[126:129], v[158:161], v[190:193], v[126:129]
	s_barrier
	s_setprio 0
	s_mov_b32 m0, s43
	ds_read_b128 v[162:165], v247 offset:16384
	ds_read_b128 v[166:169], v247 offset:18432
	ds_read_b128 v[170:173], v248 offset:16384
	ds_read_b128 v[174:177], v248 offset:18432
	ds_read_b128 v[178:181], v247 offset:20480
	ds_read_b128 v[182:185], v247 offset:22528
	ds_read_b128 v[186:189], v248 offset:20480
	ds_read_b128 v[190:193], v248 offset:22528
	buffer_load_dwordx4 v231, s[8:11], s31 offen lds
	s_mov_b32 m0, s44
	s_add_i32 s34, s31, 0x100000
	buffer_load_dwordx4 v234, s[8:11], s31 offen lds
	s_mov_b32 m0, s45
	s_nop 0
	buffer_load_dwordx4 v231, s[8:11], s34 offen lds
	s_mov_b32 m0, s47
	s_nop 0
	buffer_load_dwordx4 v234, s[8:11], s34 offen lds
	s_mov_b32 m0, s42
	s_nop 0
	buffer_load_dwordx4 v230, s[8:11], s33 offen lds
	s_mov_b32 m0, s48
	s_nop 0
	buffer_load_dwordx4 v233, s[8:11], s33 offen lds
	s_waitcnt vmcnt(8)
	s_waitcnt lgkmcnt(0)
	s_setprio 1
	s_barrier
	v_mfma_f32_16x16x32_bf16 v[10:13], v[130:133], v[162:165], v[10:13]
	v_mfma_f32_16x16x32_bf16 v[6:9], v[138:141], v[162:165], v[6:9]
	v_mfma_f32_16x16x32_bf16 v[0:3], v[130:133], v[166:169], v[2:5]
	v_mfma_f32_16x16x32_bf16 v[18:21], v[138:141], v[166:169], v[18:21]
	v_mfma_f32_16x16x32_bf16 v[14:17], v[130:133], v[178:181], v[14:17]
	v_mfma_f32_16x16x32_bf16 v[26:29], v[138:141], v[178:181], v[26:29]
	v_mfma_f32_16x16x32_bf16 v[22:25], v[130:133], v[182:185], v[22:25]
	v_mfma_f32_16x16x32_bf16 v[38:41], v[138:141], v[182:185], v[38:41]
	v_mfma_f32_16x16x32_bf16 v[10:13], v[134:137], v[170:173], v[10:13]
	v_mfma_f32_16x16x32_bf16 v[6:9], v[142:145], v[170:173], v[6:9]
	v_mfma_f32_16x16x32_bf16 v[0:3], v[134:137], v[174:177], v[0:3]
	v_mfma_f32_16x16x32_bf16 v[18:21], v[142:145], v[174:177], v[18:21]
	v_mfma_f32_16x16x32_bf16 v[14:17], v[134:137], v[186:189], v[14:17]
	v_mfma_f32_16x16x32_bf16 v[26:29], v[142:145], v[186:189], v[26:29]
	v_mfma_f32_16x16x32_bf16 v[22:25], v[134:137], v[190:193], v[22:25]
	v_mfma_f32_16x16x32_bf16 v[38:41], v[142:145], v[190:193], v[38:41]
	v_mfma_f32_16x16x32_bf16 v[34:37], v[146:149], v[162:165], v[34:37]
	v_mfma_f32_16x16x32_bf16 v[30:33], v[154:157], v[162:165], v[30:33]
	v_mfma_f32_16x16x32_bf16 v[42:45], v[146:149], v[166:169], v[42:45]
	v_mfma_f32_16x16x32_bf16 v[46:49], v[154:157], v[166:169], v[46:49]
	v_mfma_f32_16x16x32_bf16 v[50:53], v[146:149], v[178:181], v[50:53]
	v_mfma_f32_16x16x32_bf16 v[54:57], v[154:157], v[178:181], v[54:57]
	v_mfma_f32_16x16x32_bf16 v[58:61], v[146:149], v[182:185], v[58:61]
	v_mfma_f32_16x16x32_bf16 v[62:65], v[154:157], v[182:185], v[62:65]
	v_mfma_f32_16x16x32_bf16 v[34:37], v[150:153], v[170:173], v[34:37]
	v_mfma_f32_16x16x32_bf16 v[30:33], v[158:161], v[170:173], v[30:33]
	v_mfma_f32_16x16x32_bf16 v[42:45], v[150:153], v[174:177], v[42:45]
	v_mfma_f32_16x16x32_bf16 v[46:49], v[158:161], v[174:177], v[46:49]
	v_mfma_f32_16x16x32_bf16 v[50:53], v[150:153], v[186:189], v[50:53]
	v_mfma_f32_16x16x32_bf16 v[54:57], v[158:161], v[186:189], v[54:57]
	v_mfma_f32_16x16x32_bf16 v[58:61], v[150:153], v[190:193], v[58:61]
	v_mfma_f32_16x16x32_bf16 v[62:65], v[158:161], v[190:193], v[62:65]
	s_barrier
	s_setprio 0
	ds_read_b128 v[130:133], v194
	ds_read_b128 v[134:137], v195
	ds_read_b128 v[138:141], v196
	ds_read_b128 v[142:145], v197
	ds_read_b128 v[146:149], v198
	ds_read_b128 v[150:153], v199
	ds_read_b128 v[154:157], v200
	ds_read_b128 v[158:161], v201
	s_add_i32 s33, s33, 0x100000
	s_mov_b32 m0, s49
	ds_read_b128 v[162:165], v247 offset:32768
	ds_read_b128 v[166:169], v247 offset:34816
	ds_read_b128 v[170:173], v248 offset:32768
	ds_read_b128 v[174:177], v248 offset:34816
	ds_read_b128 v[178:181], v247 offset:36864
	ds_read_b128 v[182:185], v247 offset:38912
	ds_read_b128 v[186:189], v248 offset:36864
	ds_read_b128 v[190:193], v248 offset:38912
	buffer_load_dwordx4 v230, s[8:11], s33 offen lds
	s_mov_b32 m0, s50
	s_nop 0
	buffer_load_dwordx4 v233, s[8:11], s33 offen lds
	s_waitcnt vmcnt(8)
	s_waitcnt lgkmcnt(0)
	v_mfma_f32_16x16x32_bf16 v[74:77], v[130:133], v[162:165], v[74:77]
	v_mfma_f32_16x16x32_bf16 v[70:73], v[138:141], v[162:165], v[70:73]
	v_mfma_f32_16x16x32_bf16 v[66:69], v[130:133], v[166:169], v[66:69]
	v_mfma_f32_16x16x32_bf16 v[82:85], v[138:141], v[166:169], v[82:85]
	s_setprio 1
	s_barrier
	v_mfma_f32_16x16x32_bf16 v[78:81], v[130:133], v[178:181], v[78:81]
	v_mfma_f32_16x16x32_bf16 v[90:93], v[138:141], v[178:181], v[90:93]
	v_mfma_f32_16x16x32_bf16 v[86:89], v[130:133], v[182:185], v[86:89]
	v_mfma_f32_16x16x32_bf16 v[102:105], v[138:141], v[182:185], v[102:105]
	v_mfma_f32_16x16x32_bf16 v[74:77], v[134:137], v[170:173], v[74:77]
	v_mfma_f32_16x16x32_bf16 v[70:73], v[142:145], v[170:173], v[70:73]
	v_mfma_f32_16x16x32_bf16 v[66:69], v[134:137], v[174:177], v[66:69]
	v_mfma_f32_16x16x32_bf16 v[82:85], v[142:145], v[174:177], v[82:85]
	v_mfma_f32_16x16x32_bf16 v[78:81], v[134:137], v[186:189], v[78:81]
	v_mfma_f32_16x16x32_bf16 v[90:93], v[142:145], v[186:189], v[90:93]
	v_mfma_f32_16x16x32_bf16 v[86:89], v[134:137], v[190:193], v[86:89]
	v_mfma_f32_16x16x32_bf16 v[102:105], v[142:145], v[190:193], v[102:105]
	v_mfma_f32_16x16x32_bf16 v[98:101], v[146:149], v[162:165], v[98:101]
	v_mfma_f32_16x16x32_bf16 v[94:97], v[154:157], v[162:165], v[94:97]
	v_mfma_f32_16x16x32_bf16 v[106:109], v[146:149], v[166:169], v[106:109]
	v_mfma_f32_16x16x32_bf16 v[110:113], v[154:157], v[166:169], v[110:113]
	v_mfma_f32_16x16x32_bf16 v[114:117], v[146:149], v[178:181], v[114:117]
	v_mfma_f32_16x16x32_bf16 v[118:121], v[154:157], v[178:181], v[118:121]
	v_mfma_f32_16x16x32_bf16 v[122:125], v[146:149], v[182:185], v[122:125]
	v_mfma_f32_16x16x32_bf16 v[126:129], v[154:157], v[182:185], v[126:129]
	v_mfma_f32_16x16x32_bf16 v[98:101], v[150:153], v[170:173], v[98:101]
	v_mfma_f32_16x16x32_bf16 v[94:97], v[158:161], v[170:173], v[94:97]
	v_mfma_f32_16x16x32_bf16 v[106:109], v[150:153], v[174:177], v[106:109]
	v_mfma_f32_16x16x32_bf16 v[110:113], v[158:161], v[174:177], v[110:113]
	v_mfma_f32_16x16x32_bf16 v[114:117], v[150:153], v[186:189], v[114:117]
	v_mfma_f32_16x16x32_bf16 v[118:121], v[158:161], v[186:189], v[118:121]
	v_mfma_f32_16x16x32_bf16 v[122:125], v[150:153], v[190:193], v[122:125]
	v_mfma_f32_16x16x32_bf16 v[126:129], v[158:161], v[190:193], v[126:129]
	s_barrier
	s_setprio 0
	s_mov_b32 m0, s53
	s_add_i32 s33, s31, 0x80
	ds_read_b128 v[162:165], v247 offset:49152
	ds_read_b128 v[166:169], v247 offset:51200
	ds_read_b128 v[170:173], v248 offset:49152
	ds_read_b128 v[174:177], v248 offset:51200
	ds_read_b128 v[178:181], v247 offset:53248
	ds_read_b128 v[182:185], v247 offset:55296
	ds_read_b128 v[186:189], v248 offset:53248
	ds_read_b128 v[190:193], v248 offset:55296
	buffer_load_dwordx4 v231, s[8:11], s33 offen lds
	s_mov_b32 m0, s54
	s_add_i32 s31, s31, 0x100080
	buffer_load_dwordx4 v234, s[8:11], s33 offen lds
	s_mov_b32 m0, s57
	s_nop 0
	buffer_load_dwordx4 v231, s[8:11], s31 offen lds
	s_mov_b32 m0, s58
	s_nop 0
	buffer_load_dwordx4 v234, s[8:11], s31 offen lds
	s_mov_b32 m0, s55
	s_nop 0
	buffer_load_dwordx4 v230, s[8:11], s30 offen lds
	s_mov_b32 m0, s56
	s_nop 0
	buffer_load_dwordx4 v233, s[8:11], s30 offen lds
	s_waitcnt vmcnt(8)
	s_waitcnt lgkmcnt(0)
	s_setprio 1
	s_barrier
	v_mfma_f32_16x16x32_bf16 v[10:13], v[130:133], v[162:165], v[10:13]
	v_mfma_f32_16x16x32_bf16 v[4:7], v[138:141], v[162:165], v[6:9]
	v_mfma_f32_16x16x32_bf16 v[0:3], v[130:133], v[166:169], v[0:3]
	v_mfma_f32_16x16x32_bf16 v[18:21], v[138:141], v[166:169], v[18:21]
	v_mfma_f32_16x16x32_bf16 v[14:17], v[130:133], v[178:181], v[14:17]
	v_mfma_f32_16x16x32_bf16 v[26:29], v[138:141], v[178:181], v[26:29]
	v_mfma_f32_16x16x32_bf16 v[22:25], v[130:133], v[182:185], v[22:25]
	v_mfma_f32_16x16x32_bf16 v[38:41], v[138:141], v[182:185], v[38:41]
	v_mfma_f32_16x16x32_bf16 v[10:13], v[134:137], v[170:173], v[10:13]
	v_mfma_f32_16x16x32_bf16 v[6:9], v[142:145], v[170:173], v[4:7]
	v_mfma_f32_16x16x32_bf16 v[2:5], v[134:137], v[174:177], v[0:3]
	v_mfma_f32_16x16x32_bf16 v[18:21], v[142:145], v[174:177], v[18:21]
	v_mfma_f32_16x16x32_bf16 v[14:17], v[134:137], v[186:189], v[14:17]
	v_mfma_f32_16x16x32_bf16 v[26:29], v[142:145], v[186:189], v[26:29]
	v_mfma_f32_16x16x32_bf16 v[22:25], v[134:137], v[190:193], v[22:25]
	v_mfma_f32_16x16x32_bf16 v[38:41], v[142:145], v[190:193], v[38:41]
	v_mfma_f32_16x16x32_bf16 v[34:37], v[146:149], v[162:165], v[34:37]
	v_mfma_f32_16x16x32_bf16 v[30:33], v[154:157], v[162:165], v[30:33]
	v_mfma_f32_16x16x32_bf16 v[42:45], v[146:149], v[166:169], v[42:45]
	v_mfma_f32_16x16x32_bf16 v[46:49], v[154:157], v[166:169], v[46:49]
	v_mfma_f32_16x16x32_bf16 v[50:53], v[146:149], v[178:181], v[50:53]
	v_mfma_f32_16x16x32_bf16 v[54:57], v[154:157], v[178:181], v[54:57]
	v_mfma_f32_16x16x32_bf16 v[58:61], v[146:149], v[182:185], v[58:61]
	v_mfma_f32_16x16x32_bf16 v[62:65], v[154:157], v[182:185], v[62:65]
	v_mfma_f32_16x16x32_bf16 v[34:37], v[150:153], v[170:173], v[34:37]
	v_mfma_f32_16x16x32_bf16 v[30:33], v[158:161], v[170:173], v[30:33]
	v_mfma_f32_16x16x32_bf16 v[42:45], v[150:153], v[174:177], v[42:45]
	v_mfma_f32_16x16x32_bf16 v[46:49], v[158:161], v[174:177], v[46:49]
	v_mfma_f32_16x16x32_bf16 v[50:53], v[150:153], v[186:189], v[50:53]
	v_mfma_f32_16x16x32_bf16 v[54:57], v[158:161], v[186:189], v[54:57]
	v_mfma_f32_16x16x32_bf16 v[58:61], v[150:153], v[190:193], v[58:61]
	v_mfma_f32_16x16x32_bf16 v[62:65], v[158:161], v[190:193], v[62:65]
	s_barrier
	s_setprio 0
	s_add_i32 s4, s4, 2
	s_addk_i32 s5, 0x100
	s_cmp_gt_u32 s4, 61
	s_cbranch_scc0 .LBB0_1251
	s_and_b64 vcc, exec, s[18:19]
	s_cbranch_vccz .LBB0_1254
	s_barrier
